# v25 + the five GEMM K-loop heads aligned to 64 bytes (.p2align 6)
# baseline (speedup 1.0000x reference)
; template <class Epi, class Sched, bool ALIGN_EPI = false, bool SP2 = false>
; __device__ __forceinline__ void gemm_phase(PG8_LAS unsigned char* lds, const Gemm g, const Sched& S, const Epi& E) {
;     ...
;         const bool has_next = S.next(ui + 1, nxt);
;         const char* nA = has_next ? (const char*)g.A + (size_t)nxt.pm * tstep : cA; const char* nB = has_next ? (const char*)g.Bt + (size_t)nxt.pn * tstep : cB;
;         for (int t = 0; t < nt; t += 2) {
;             if constexpr (Epi::HAS_MID) { if (t == nt / 2) E.mid(acc, cur, wr, wc, fr, fq); }
;             const bool last = (t == nt - 2);
;             const char* a1 = cA + (size_t)(t + 1) * kstep;
;             const char* a2 = last ? nA : cA + (size_t)(t + 2) * kstep; const char* b2 = last ? nB : cB + (size_t)(t + 2) * kstep;
;             const char* a3 = a2 + kstep; const char* b3 = b2 + kstep;
;     ...
; #pragma unroll
;         for (int a = 0; a < 2; ++a)
; #pragma unroll
;             for (int b = 0; b < 2; ++b)
; #pragma unroll
;                 for (int m = 0; m < 4; ++m)
; #pragma unroll
;                     for (int n = 0; n < 2; ++n) acc[a][b][m][n] = (f32x4){0.f, 0.f, 0.f, 0.f};
.LBB0_191:
	s_ashr_i32 s13, s12, 31
	s_lshl_b64 s[14:15], s[12:13], 19
	v_readlane_b32 s16, v241, 53
	v_readlane_b32 s17, v241, 54
	s_add_u32 s14, s16, s14
	s_addc_u32 s15, s17, s15
	s_and_b64 s[16:17], s[2:3], exec
	s_cselect_b32 s5, s15, s21
	s_cselect_b32 s13, s14, s20
	s_ashr_i32 s11, s10, 31
	s_lshl_b64 s[16:17], s[10:11], 19
	v_readlane_b32 s24, v241, 36
	v_readlane_b32 s25, v241, 37
	s_add_u32 s16, s24, s16
	s_addc_u32 s17, s25, s17
	s_and_b64 s[24:25], s[2:3], exec
	s_cselect_b32 s11, s17, s23
	s_cselect_b32 s19, s16, s22
	s_add_u32 s20, s20, 0x40080
	s_addc_u32 s21, s21, 0
	s_add_u32 s73, s22, 0x100
	v_mov_b32_e32 v2, 0
	s_addc_u32 s74, s23, 0
	s_mov_b32 s75, -2
	v_mov_b32_e32 v3, 0
	v_mov_b64_e32 v[4:5], 0
	v_mov_b64_e32 v[6:7], 0
	v_mov_b64_e32 v[8:9], 0
	v_mov_b64_e32 v[14:15], 0
	v_mov_b64_e32 v[16:17], 0
	v_mov_b64_e32 v[22:23], 0
	v_mov_b64_e32 v[24:25], 0
	v_mov_b64_e32 v[30:31], 0
	v_mov_b64_e32 v[32:33], 0
	v_mov_b64_e32 v[38:39], 0
	v_mov_b64_e32 v[40:41], 0
	v_mov_b64_e32 v[46:47], 0
	v_mov_b64_e32 v[48:49], 0
	v_mov_b64_e32 v[54:55], 0
	v_mov_b64_e32 v[56:57], 0
	v_mov_b64_e32 v[10:11], 0
	v_mov_b64_e32 v[12:13], 0
	v_mov_b64_e32 v[18:19], 0
	v_mov_b64_e32 v[20:21], 0
	v_mov_b64_e32 v[26:27], 0
	v_mov_b64_e32 v[28:29], 0
	v_mov_b64_e32 v[34:35], 0
	v_mov_b64_e32 v[36:37], 0
	v_mov_b64_e32 v[42:43], 0
	v_mov_b64_e32 v[44:45], 0
	v_mov_b64_e32 v[50:51], 0
	v_mov_b64_e32 v[52:53], 0
	v_mov_b64_e32 v[58:59], 0
	v_mov_b64_e32 v[60:61], 0
	v_mov_b64_e32 v[62:63], 0
	v_mov_b64_e32 v[64:65], 0
	v_mov_b64_e32 v[66:67], 0
	v_mov_b64_e32 v[68:69], 0
	v_mov_b64_e32 v[70:71], 0
	v_mov_b64_e32 v[72:73], 0
	v_mov_b64_e32 v[78:79], 0
	v_mov_b64_e32 v[80:81], 0
	v_mov_b64_e32 v[86:87], 0
	v_mov_b64_e32 v[88:89], 0
	v_mov_b64_e32 v[94:95], 0
	v_mov_b64_e32 v[96:97], 0
	v_mov_b64_e32 v[102:103], 0
	v_mov_b64_e32 v[104:105], 0
	v_mov_b64_e32 v[110:111], 0
	v_mov_b64_e32 v[112:113], 0
	v_mov_b64_e32 v[118:119], 0
	v_mov_b64_e32 v[120:121], 0
	v_mov_b64_e32 v[74:75], 0
	v_mov_b64_e32 v[76:77], 0
	v_mov_b64_e32 v[82:83], 0
	v_mov_b64_e32 v[84:85], 0
	v_mov_b64_e32 v[90:91], 0
	v_mov_b64_e32 v[92:93], 0
	v_mov_b64_e32 v[98:99], 0
	v_mov_b64_e32 v[100:101], 0
	v_mov_b64_e32 v[106:107], 0
	v_mov_b64_e32 v[108:109], 0
	v_mov_b64_e32 v[114:115], 0
	v_mov_b64_e32 v[116:117], 0
	v_mov_b64_e32 v[122:123], 0
	v_mov_b64_e32 v[124:125], 0
	v_mov_b64_e32 v[126:127], 0
	v_mov_b64_e32 v[128:129], 0
	.p2align 6

; template <class Epi, class Sched, bool ALIGN_EPI = false, bool SP2 = false>
; __device__ __forceinline__ void gemm_phase(PG8_LAS unsigned char* lds, const Gemm g, const Sched& S, const Epi& E) {
;     ...
;         const bool has_next = S.next(ui + 1, nxt);
;         const char* nA = has_next ? (const char*)g.A + (size_t)nxt.pm * tstep : cA; const char* nB = has_next ? (const char*)g.Bt + (size_t)nxt.pn * tstep : cB;
;         for (int t = 0; t < nt; t += 2) {
;             if constexpr (Epi::HAS_MID) { if (t == nt / 2) E.mid(acc, cur, wr, wc, fr, fq); }
;             const bool last = (t == nt - 2);
;             const char* a1 = cA + (size_t)(t + 1) * kstep;
;             const char* a2 = last ? nA : cA + (size_t)(t + 2) * kstep; const char* b2 = last ? nB : cB + (size_t)(t + 2) * kstep;
;             const char* a3 = a2 + kstep; const char* b3 = b2 + kstep;
;     ...
; #pragma unroll
;         for (int a = 0; a < 2; ++a)
; #pragma unroll
;             for (int b = 0; b < 2; ++b)
; #pragma unroll
;                 for (int m = 0; m < 4; ++m)
; #pragma unroll
;                     for (int n = 0; n < 2; ++n) acc[a][b][m][n] = (f32x4){0.f, 0.f, 0.f, 0.f};
.LBB0_1093:
	s_ashr_i32 s17, s16, 31
	s_lshl_b64 s[18:19], s[16:17], 19
	v_readlane_b32 s20, v240, 14
	v_readlane_b32 s21, v240, 15
	s_add_u32 s18, s20, s18
	s_addc_u32 s19, s21, s19
	s_and_b64 s[20:21], s[2:3], exec
	s_cselect_b32 s17, s19, s23
	s_cselect_b32 s54, s18, s22
	s_ashr_i32 s15, s14, 31
	s_lshl_b64 s[20:21], s[14:15], 19
	v_readlane_b32 s28, v241, 38
	v_readlane_b32 s29, v241, 39
	s_add_u32 s20, s28, s20
	s_addc_u32 s21, s29, s21
	s_and_b64 s[28:29], s[2:3], exec
	s_cselect_b32 s56, s21, s27
	s_cselect_b32 s57, s20, s26
	s_lshl_b32 s15, s24, 8
	s_lshl_b32 s55, s25, 8
	s_add_i32 s60, s15, s38
	s_or_b32 s61, s55, s43
	v_mov_b32_e32 v4, v2
	v_mov_b32_e32 v5, v2
	s_add_u32 s62, s26, 0x100
	v_mov_b32_e32 v3, v2
	v_mov_b64_e32 v[8:9], v[4:5]
	v_mov_b64_e32 v[12:13], v[4:5]
	v_mov_b64_e32 v[24:25], v[4:5]
	v_mov_b64_e32 v[28:29], v[4:5]
	v_mov_b64_e32 v[40:41], v[4:5]
	v_mov_b64_e32 v[44:45], v[4:5]
	v_mov_b64_e32 v[56:57], v[4:5]
	v_mov_b64_e32 v[60:61], v[4:5]
	v_mov_b64_e32 v[16:17], v[4:5]
	v_mov_b64_e32 v[20:21], v[4:5]
	v_mov_b64_e32 v[32:33], v[4:5]
	v_mov_b64_e32 v[36:37], v[4:5]
	v_mov_b64_e32 v[48:49], v[4:5]
	v_mov_b64_e32 v[52:53], v[4:5]
	v_mov_b64_e32 v[64:65], v[4:5]
	v_mov_b64_e32 v[68:69], v[4:5]
	v_mov_b64_e32 v[72:73], v[4:5]
	v_mov_b64_e32 v[76:77], v[4:5]
	v_mov_b64_e32 v[88:89], v[4:5]
	v_mov_b64_e32 v[92:93], v[4:5]
	v_mov_b64_e32 v[104:105], v[4:5]
	v_mov_b64_e32 v[108:109], v[4:5]
	v_mov_b64_e32 v[120:121], v[4:5]
	v_mov_b64_e32 v[124:125], v[4:5]
	v_mov_b64_e32 v[80:81], v[4:5]
	v_mov_b64_e32 v[84:85], v[4:5]
	v_mov_b64_e32 v[96:97], v[4:5]
	v_mov_b64_e32 v[100:101], v[4:5]
	v_mov_b64_e32 v[112:113], v[4:5]
	v_mov_b64_e32 v[116:117], v[4:5]
	v_mov_b64_e32 v[128:129], v[4:5]
	v_mov_b64_e32 v[132:133], v[4:5]
	v_lshl_add_u64 v[214:215], s[22:23], 0, v[206:207]
	v_lshl_add_u64 v[216:217], s[22:23], 0, v[208:209]
	s_addc_u32 s63, s27, 0
	s_mov_b32 s64, -2
	s_mov_b64 s[24:25], 0
	v_mov_b64_e32 v[6:7], v[2:3]
	v_mov_b64_e32 v[10:11], v[2:3]
	v_mov_b64_e32 v[22:23], v[2:3]
	v_mov_b64_e32 v[26:27], v[2:3]
	v_mov_b64_e32 v[38:39], v[2:3]
	v_mov_b64_e32 v[42:43], v[2:3]
	v_mov_b64_e32 v[54:55], v[2:3]
	v_mov_b64_e32 v[58:59], v[2:3]
	v_mov_b64_e32 v[14:15], v[2:3]
	v_mov_b64_e32 v[18:19], v[2:3]
	v_mov_b64_e32 v[30:31], v[2:3]
	v_mov_b64_e32 v[34:35], v[2:3]
	v_mov_b64_e32 v[46:47], v[2:3]
	v_mov_b64_e32 v[50:51], v[2:3]
	v_mov_b64_e32 v[62:63], v[2:3]
	v_mov_b64_e32 v[66:67], v[2:3]
	v_mov_b64_e32 v[70:71], v[2:3]
	v_mov_b64_e32 v[74:75], v[2:3]
	v_mov_b64_e32 v[86:87], v[2:3]
	v_mov_b64_e32 v[90:91], v[2:3]
	v_mov_b64_e32 v[102:103], v[2:3]
	v_mov_b64_e32 v[106:107], v[2:3]
	v_mov_b64_e32 v[118:119], v[2:3]
	v_mov_b64_e32 v[122:123], v[2:3]
	v_mov_b64_e32 v[78:79], v[2:3]
	v_mov_b64_e32 v[82:83], v[2:3]
	v_mov_b64_e32 v[94:95], v[2:3]
	v_mov_b64_e32 v[98:99], v[2:3]
	v_mov_b64_e32 v[110:111], v[2:3]
	v_mov_b64_e32 v[114:115], v[2:3]
	v_mov_b64_e32 v[126:127], v[2:3]
	v_mov_b64_e32 v[130:131], v[2:3]
	s_branch .LBB0_1095
	.p2align 6

; template <class Epi, class Sched, bool ALIGN_EPI = false, bool SP2 = false>
; __device__ __forceinline__ void gemm_phase(PG8_LAS unsigned char* lds, const Gemm g, const Sched& S, const Epi& E) {
;     ...
;         const bool has_next = S.next(ui + 1, nxt);
;         const char* nA = has_next ? (const char*)g.A + (size_t)nxt.pm * tstep : cA; const char* nB = has_next ? (const char*)g.Bt + (size_t)nxt.pn * tstep : cB;
;         for (int t = 0; t < nt; t += 2) {
;             if constexpr (Epi::HAS_MID) { if (t == nt / 2) E.mid(acc, cur, wr, wc, fr, fq); }
;             const bool last = (t == nt - 2);
;             const char* a1 = cA + (size_t)(t + 1) * kstep;
;             const char* a2 = last ? nA : cA + (size_t)(t + 2) * kstep; const char* b2 = last ? nB : cB + (size_t)(t + 2) * kstep;
;             const char* a3 = a2 + kstep; const char* b3 = b2 + kstep;
.LBB0_1179:
	s_add_u32 s25, s28, 0x100
	s_addc_u32 s57, s29, 0
	s_ashr_i32 s21, s20, 31
	s_lshl_b64 s[22:23], s[20:21], 19
	s_add_u32 s26, s94, s22
	s_addc_u32 s27, s95, s23
	s_and_b64 s[22:23], s[8:9], exec
	s_cselect_b32 s21, s27, s11
	s_cselect_b32 s58, s26, s10
	s_ashr_i32 s19, s18, 31
	s_lshl_b64 s[22:23], s[18:19], 19
	v_readlane_b32 s34, v241, 40
	v_readlane_b32 s35, v241, 41
	s_add_u32 s22, s34, s22
	s_addc_u32 s23, s35, s23
	s_and_b64 s[34:35], s[8:9], exec
	s_cselect_b32 s19, s23, s29
	s_cselect_b32 s59, s22, s28
	v_lshl_add_u64 v[138:139], s[10:11], 0, v[130:131]
	v_lshl_add_u64 v[140:141], s[10:11], 0, v[132:133]
	s_mov_b32 s60, -2
	s_mov_b64 s[28:29], 0
	.p2align 6

; template <class Epi, class Sched, bool ALIGN_EPI = false, bool SP2 = false>
; __device__ __forceinline__ void gemm_phase(PG8_LAS unsigned char* lds, const Gemm g, const Sched& S, const Epi& E) {
;     ...
;         const bool has_next = S.next(ui + 1, nxt);
;         const char* nA = has_next ? (const char*)g.A + (size_t)nxt.pm * tstep : cA; const char* nB = has_next ? (const char*)g.Bt + (size_t)nxt.pn * tstep : cB;
;         for (int t = 0; t < nt; t += 2) {
;             if constexpr (Epi::HAS_MID) { if (t == nt / 2) E.mid(acc, cur, wr, wc, fr, fq); }
;             const bool last = (t == nt - 2);
;             const char* a1 = cA + (size_t)(t + 1) * kstep;
;             const char* a2 = last ? nA : cA + (size_t)(t + 2) * kstep; const char* b2 = last ? nB : cB + (size_t)(t + 2) * kstep;
;             const char* a3 = a2 + kstep; const char* b3 = b2 + kstep;
;     ...
; #pragma unroll
;         for (int a = 0; a < 2; ++a)
; #pragma unroll
;             for (int b = 0; b < 2; ++b)
; #pragma unroll
;                 for (int m = 0; m < 4; ++m)
; #pragma unroll
;                     for (int n = 0; n < 2; ++n) acc[a][b][m][n] = (f32x4){0.f, 0.f, 0.f, 0.f};
.LBB0_1312:
	s_ashr_i32 s27, s26, 31
	s_lshl_b64 s[28:29], s[26:27], 19
	s_add_u32 s28, s12, s28
	s_addc_u32 s29, s13, s29
	s_and_b64 s[34:35], s[6:7], exec
	s_cselect_b32 s9, s29, s39
	s_cselect_b32 s27, s28, s38
	s_ashr_i32 s25, s24, 31
	s_lshl_b64 s[34:35], s[24:25], 19
	s_add_u32 s34, s78, s34
	s_addc_u32 s35, s79, s35
	s_and_b64 s[42:43], s[6:7], exec
	s_cselect_b32 s25, s35, s41
	s_cselect_b32 s37, s34, s40
	s_add_u32 s38, s38, 0x40080
	s_addc_u32 s39, s39, 0
	s_add_u32 s59, s40, 0x100
	v_mov_b32_e32 v2, 0
	s_addc_u32 s60, s41, 0
	s_mov_b32 s61, -2
	v_mov_b32_e32 v3, 0
	v_mov_b64_e32 v[4:5], 0
	v_mov_b64_e32 v[6:7], 0
	v_mov_b64_e32 v[8:9], 0
	v_mov_b64_e32 v[18:19], 0
	v_mov_b64_e32 v[20:21], 0
	v_mov_b64_e32 v[22:23], 0
	v_mov_b64_e32 v[24:25], 0
	v_mov_b64_e32 v[34:35], 0
	v_mov_b64_e32 v[36:37], 0
	v_mov_b64_e32 v[38:39], 0
	v_mov_b64_e32 v[40:41], 0
	v_mov_b64_e32 v[50:51], 0
	v_mov_b64_e32 v[52:53], 0
	v_mov_b64_e32 v[54:55], 0
	v_mov_b64_e32 v[56:57], 0
	v_mov_b64_e32 v[10:11], 0
	v_mov_b64_e32 v[12:13], 0
	v_mov_b64_e32 v[14:15], 0
	v_mov_b64_e32 v[16:17], 0
	v_mov_b64_e32 v[26:27], 0
	v_mov_b64_e32 v[28:29], 0
	v_mov_b64_e32 v[30:31], 0
	v_mov_b64_e32 v[32:33], 0
	v_mov_b64_e32 v[42:43], 0
	v_mov_b64_e32 v[44:45], 0
	v_mov_b64_e32 v[46:47], 0
	v_mov_b64_e32 v[48:49], 0
	v_mov_b64_e32 v[58:59], 0
	v_mov_b64_e32 v[60:61], 0
	v_mov_b64_e32 v[62:63], 0
	v_mov_b64_e32 v[64:65], 0
	v_mov_b64_e32 v[66:67], 0
	v_mov_b64_e32 v[68:69], 0
	v_mov_b64_e32 v[70:71], 0
	v_mov_b64_e32 v[72:73], 0
	v_mov_b64_e32 v[82:83], 0
	v_mov_b64_e32 v[84:85], 0
	v_mov_b64_e32 v[86:87], 0
	v_mov_b64_e32 v[88:89], 0
	v_mov_b64_e32 v[98:99], 0
	v_mov_b64_e32 v[100:101], 0
	v_mov_b64_e32 v[102:103], 0
	v_mov_b64_e32 v[104:105], 0
	v_mov_b64_e32 v[114:115], 0
	v_mov_b64_e32 v[116:117], 0
	v_mov_b64_e32 v[118:119], 0
	v_mov_b64_e32 v[120:121], 0
	v_mov_b64_e32 v[74:75], 0
	v_mov_b64_e32 v[76:77], 0
	v_mov_b64_e32 v[78:79], 0
	v_mov_b64_e32 v[80:81], 0
	v_mov_b64_e32 v[90:91], 0
	v_mov_b64_e32 v[92:93], 0
	v_mov_b64_e32 v[94:95], 0
	v_mov_b64_e32 v[96:97], 0
	v_mov_b64_e32 v[106:107], 0
	v_mov_b64_e32 v[108:109], 0
	v_mov_b64_e32 v[110:111], 0
	v_mov_b64_e32 v[112:113], 0
	v_mov_b64_e32 v[122:123], 0
	v_mov_b64_e32 v[124:125], 0
	v_mov_b64_e32 v[126:127], 0
	v_mov_b64_e32 v[128:129], 0
	.p2align 6

; template <class Epi, class Sched, bool ALIGN_EPI = false, bool SP2 = false>
; __device__ __forceinline__ void gemm_phase(PG8_LAS unsigned char* lds, const Gemm g, const Sched& S, const Epi& E) {
;     ...
;         const bool has_next = S.next(ui + 1, nxt);
;         const char* nA = has_next ? (const char*)g.A + (size_t)nxt.pm * tstep : cA; const char* nB = has_next ? (const char*)g.Bt + (size_t)nxt.pn * tstep : cB;
;         for (int t = 0; t < nt; t += 2) {
;             if constexpr (Epi::HAS_MID) { if (t == nt / 2) E.mid(acc, cur, wr, wc, fr, fq); }
;             const bool last = (t == nt - 2);
;             const char* a1 = cA + (size_t)(t + 1) * kstep;
;             const char* a2 = last ? nA : cA + (size_t)(t + 2) * kstep; const char* b2 = last ? nB : cB + (size_t)(t + 2) * kstep;
;             const char* a3 = a2 + kstep; const char* b3 = b2 + kstep;
.LBB0_1428:
	s_add_u32 s21, s24, 0x100
	s_addc_u32 s45, s25, 0
	s_ashr_i32 s17, s16, 31
	s_lshl_b64 s[18:19], s[16:17], 21
	s_add_u32 s22, s52, s18
	s_addc_u32 s23, s53, s19
	s_and_b64 s[18:19], s[2:3], exec
	s_cselect_b32 s17, s23, s9
	s_cselect_b32 s46, s22, s8
	s_ashr_i32 s15, s14, 31
	s_lshl_b64 s[18:19], s[14:15], 21
	s_add_u32 s18, s68, s18
	s_addc_u32 s19, s69, s19
	s_and_b64 s[26:27], s[2:3], exec
	s_cselect_b32 s15, s19, s25
	s_cselect_b32 s47, s18, s24
	v_lshl_add_u64 v[146:147], s[8:9], 0, v[138:139]
	v_lshl_add_u64 v[148:149], s[8:9], 0, v[140:141]
	s_mov_b32 s54, -2
	s_mov_b64 s[24:25], 0
	.p2align 6
